# NSA prep: all later global loads of an item issued behind the first block (one exposed latency per item instead of seven)
# speedup vs baseline: 1.1539x; 1.0046x over previous
; DI unsigned pk2(float lo, float hi) { f32x2 v = {lo, hi}; bf16x2_t r = __builtin_convertvector(v, bf16x2_t); return __builtin_bit_cast(unsigned, r); }
; DI void phase_nsa_prep(const Params& p, int l, char* smem) {
;     ...
; #pragma unroll
;         for (int w = 0; w < 2; ++w) {
;             const bf16_t* src = pr + C_KV + (w == 0 ? 256 : 512) + kvh * 64 + part * 16;
;             const float* g = p.k_norm + (l * 3 + 1 + w) * 64 + part * 16;
;             float v[16]; float ss = 0.f;
;             { const u32x4 a0 = *(const u32x4*)src, a1 = *(const u32x4*)(src + 8);
; #pragma unroll
;               for (int j = 0; j < 4; ++j) { v[2 * j] = __uint_as_float(a0[j] << 16); v[2 * j + 1] = __uint_as_float(a0[j] & 0xffff0000u);
;                                             v[8 + 2 * j] = __uint_as_float(a1[j] << 16); v[9 + 2 * j] = __uint_as_float(a1[j] & 0xffff0000u); } }
; #pragma unroll
;             for (int j = 0; j < 16; ++j) ss += v[j] * v[j];
;             ss += __shfl_xor(ss, 1); ss += __shfl_xor(ss, 2);
;             const float r = rsqrtf(ss * (1.f / 64.f) + 1e-6f);
;             bf16_t* dst = (w == 0 ? p.ksn : p.kwn) + (((size_t)(b * 2 + kvh) * T_) + blk * 64 + t) * 64 + part * 16;
;             u32x4 o0, o1;
; #pragma unroll
;             for (int j = 0; j < 4; ++j) { o0[j] = pk2(v[2 * j] * r * g[2 * j], v[2 * j + 1] * r * g[2 * j + 1]); o1[j] = pk2(v[8 + 2 * j] * r * g[8 + 2 * j], v[9 + 2 * j] * r * g[9 + 2 * j]); }
;             *(u32x4*)dst = o0; *(u32x4*)(dst + 8) = o1;
;         }
.LBB0_350:
	s_ashr_i32 s4, s7, 9
	s_ashr_i32 s5, s4, 31
	s_and_b32 s30, s6, 0x3fc0
	s_lshl_b64 s[10:11], s[4:5], 14
	v_lshl_add_u64 v[2:3], s[30:31], 0, v[8:9]
	v_lshl_add_u64 v[20:21], v[2:3], 0, s[10:11]
	v_mov_b64_e32 v[0:1], s[12:13]
	s_bfe_u32 s9, s7, 0x10008
	v_mad_u64_u32 v[0:1], s[10:11], v20, s41, v[0:1]
	v_mad_i32_i24 v1, v21, s41, v1
	s_lshl_b32 s30, s9, 7
	v_lshl_add_u64 v[4:5], v[0:1], 0, s[30:31]
	v_lshl_add_u64 v[4:5], v[4:5], 0, v[188:189]
	s_mov_b64 s[10:11], 0xf80
	v_lshl_add_u64 v[18:19], v[4:5], 0, s[10:11]
	v_lshlrev_b64 v[16:17], 7, v[2:3]
	global_load_dwordx4 v[2:5], v[18:19], off offset:512
	global_load_dwordx4 v[22:25], v[18:19], off offset:528
	global_load_dwordx4 v[36:39], v[10:11], off offset:304
	global_load_dwordx4 v[40:43], v[10:11], off offset:288
	global_load_dwordx4 v[44:47], v[10:11], off offset:272
	global_load_dwordx4 v[48:51], v[10:11], off offset:256
	v_lshl_add_u64 v[192:193], v[0:1], 0, v[188:189]
	s_mul_i32 s98, s9, 0x180
	s_mov_b32 s99, 0
	s_nop 0
	v_lshl_add_u64 v[192:193], v[192:193], 0, s[98:99]
	global_load_dwordx4 v[76:79], v[18:19], off offset:1024
	global_load_dwordx4 v[80:83], v[18:19], off offset:1040
	global_load_dwordx4 v[84:87], v[10:11], off offset:560
	global_load_dwordx4 v[88:91], v[10:11], off offset:544
	global_load_dwordx4 v[92:95], v[10:11], off offset:528
	global_load_dwordx4 v[96:99], v[10:11], off offset:512
	global_load_dwordx4 v[100:103], v[192:193], off offset:3200
	global_load_dwordx4 v[104:107], v[192:193], off offset:3216
	global_load_dwordx4 v[108:111], v[12:13], off offset:48
	global_load_dwordx4 v[112:115], v[12:13], off offset:32
	global_load_dwordx4 v[116:119], v[12:13], off offset:16
	global_load_dwordx4 v[120:123], v[12:13], off
	global_load_dwordx4 v[124:127], v[192:193], off offset:3328
	global_load_dwordx4 v[128:131], v[192:193], off offset:3344
	global_load_dwordx4 v[132:135], v[12:13], off offset:48
	global_load_dwordx4 v[136:139], v[12:13], off offset:32
	global_load_dwordx4 v[140:143], v[12:13], off offset:16
	global_load_dwordx4 v[144:147], v[12:13], off
	global_load_dwordx4 v[148:151], v[192:193], off offset:3456
	global_load_dwordx4 v[152:155], v[192:193], off offset:3472
	global_load_dwordx4 v[156:159], v[12:13], off offset:48
	global_load_dwordx4 v[160:163], v[12:13], off offset:32
	global_load_dwordx4 v[164:167], v[12:13], off offset:16
	global_load_dwordx4 v[168:171], v[12:13], off
	global_load_dwordx4 v[172:175], v[18:19], off offset:768
	global_load_dwordx4 v[176:179], v[18:19], off offset:784
	global_load_dwordx4 v[180:183], v[18:19], off offset:1280
	global_load_dwordx4 v[184:187], v[18:19], off offset:1296
	s_lshl_b32 s4, s4, 1
	s_or_b32 s4, s4, s9
	s_ashr_i32 s5, s4, 31
	s_lshl_b64 s[4:5], s[4:5], 21
	s_add_u32 s10, s52, s4
	s_addc_u32 s11, s53, s5
	v_lshl_add_u64 v[6:7], s[10:11], 0, v[16:17]
	v_lshl_add_u64 v[6:7], v[6:7], 0, v[188:189]
	s_add_u32 s10, s54, s4
	s_addc_u32 s11, s55, s5
	s_mul_i32 s30, s9, 0x180
	s_mul_i32 s8, s9, 3
	s_add_i32 s9, s8, 1
	s_waitcnt vmcnt(33)
	v_lshlrev_b32_e32 v74, 16, v2
	v_and_b32_e32 v75, 0xffff0000, v2
	v_lshlrev_b32_e32 v68, 16, v3
	v_and_b32_e32 v69, 0xffff0000, v3
	v_pk_mul_f32 v[2:3], v[74:75], v[74:75]
	v_pk_mul_f32 v[70:71], v[68:69], v[68:69]
	v_add_f32_e32 v2, v2, v3
	v_lshlrev_b32_e32 v62, 16, v4
	v_and_b32_e32 v63, 0xffff0000, v4
	v_add_f32_e32 v2, v70, v2
	v_lshlrev_b32_e32 v56, 16, v5
	v_and_b32_e32 v57, 0xffff0000, v5
	v_pk_mul_f32 v[4:5], v[62:63], v[62:63]
	v_add_f32_e32 v2, v71, v2
	v_add_f32_e32 v2, v4, v2
	v_pk_mul_f32 v[58:59], v[56:57], v[56:57]
	v_add_f32_e32 v2, v5, v2
	s_waitcnt vmcnt(32)
	v_lshlrev_b32_e32 v72, 16, v22
	v_and_b32_e32 v73, 0xffff0000, v22
	v_add_f32_e32 v2, v58, v2
	v_lshlrev_b32_e32 v64, 16, v23
	v_and_b32_e32 v65, 0xffff0000, v23
	v_pk_mul_f32 v[22:23], v[72:73], v[72:73]
	v_add_f32_e32 v2, v59, v2
	v_add_f32_e32 v2, v22, v2
	v_pk_mul_f32 v[66:67], v[64:65], v[64:65]
	v_add_f32_e32 v2, v23, v2
	v_lshlrev_b32_e32 v60, 16, v24
	v_and_b32_e32 v61, 0xffff0000, v24
	v_add_f32_e32 v2, v66, v2
	v_lshlrev_b32_e32 v52, 16, v25
	v_and_b32_e32 v53, 0xffff0000, v25
	v_pk_mul_f32 v[24:25], v[60:61], v[60:61]
	v_add_f32_e32 v2, v67, v2
	v_add_f32_e32 v2, v24, v2
	v_pk_mul_f32 v[54:55], v[52:53], v[52:53]
	v_add_f32_e32 v2, v25, v2
	v_add_f32_e32 v2, v54, v2
	v_add_f32_e32 v2, v55, v2
	ds_bpermute_b32 v3, v26, v2
	s_waitcnt lgkmcnt(0)
	v_add_f32_e32 v2, v2, v3
	ds_bpermute_b32 v3, v27, v2
	s_waitcnt lgkmcnt(0)
	v_add_f32_e32 v2, v2, v3
	v_fmamk_f32 v2, v2, 0x3c800000, v212
	v_cmp_gt_f32_e32 vcc, s16, v2
	v_mul_f32_e32 v3, 0x4b800000, v2
	s_nop 0
	v_cndmask_b32_e32 v2, v2, v3, vcc
	v_rsq_f32_e32 v2, v2
	s_nop 0
	v_mul_f32_e32 v3, 0x45800000, v2
	v_cndmask_b32_e32 v54, v2, v3, vcc
	v_pk_mul_f32 v[4:5], v[54:55], v[72:73] op_sel_hi:[0,1]
	s_waitcnt vmcnt(30)
	v_pk_mul_f32 v[4:5], v[40:41], v[4:5]
	v_pk_mul_f32 v[2:3], v[54:55], v[74:75] op_sel_hi:[0,1]
	v_cvt_pk_bf16_f32 v22, v4, v5
	v_pk_mul_f32 v[4:5], v[54:55], v[68:69] op_sel_hi:[0,1]
	s_waitcnt vmcnt(28)
	v_pk_mul_f32 v[2:3], v[48:49], v[2:3]
	v_pk_mul_f32 v[4:5], v[50:51], v[4:5]
	v_cvt_pk_bf16_f32 v2, v2, v3
	v_cvt_pk_bf16_f32 v3, v4, v5
	v_pk_mul_f32 v[4:5], v[54:55], v[64:65] op_sel_hi:[0,1]
	v_pk_mul_f32 v[4:5], v[42:43], v[4:5]
	v_pk_mul_f32 v[24:25], v[54:55], v[60:61] op_sel_hi:[0,1]
	v_cvt_pk_bf16_f32 v23, v4, v5
	v_pk_mul_f32 v[4:5], v[54:55], v[62:63] op_sel_hi:[0,1]
	v_pk_mul_f32 v[24:25], v[36:37], v[24:25]
	v_pk_mul_f32 v[36:37], v[54:55], v[56:57] op_sel_hi:[0,1]
	v_pk_mul_f32 v[4:5], v[44:45], v[4:5]
	v_pk_mul_f32 v[36:37], v[46:47], v[36:37]
	v_cvt_pk_bf16_f32 v4, v4, v5
	v_cvt_pk_bf16_f32 v5, v36, v37
	v_pk_mul_f32 v[36:37], v[54:55], v[52:53] op_sel_hi:[0,1]
	v_pk_mul_f32 v[36:37], v[38:39], v[36:37]
	v_cvt_pk_bf16_f32 v24, v24, v25
	v_cvt_pk_bf16_f32 v25, v36, v37
	global_store_dwordx4 v[6:7], v[2:5], off
	global_store_dwordx4 v[6:7], v[22:25], off offset:16
	s_waitcnt vmcnt(2)
; DI void phase_nsa_prep(const Params& p, int l, char* smem) {
;     ...
;         for (int w = 0; w < 2; ++w) {
;             const bf16_t* src = pr + C_KV + (w == 0 ? 256 : 512) + kvh * 64 + part * 16;
;             const float* g = p.k_norm + (l * 3 + 1 + w) * 64 + part * 16;
;             float v[16]; float ss = 0.f;
;             { const u32x4 a0 = *(const u32x4*)src, a1 = *(const u32x4*)(src + 8);
; #pragma unroll
;               for (int j = 0; j < 4; ++j) { v[2 * j] = __uint_as_float(a0[j] << 16); v[2 * j + 1] = __uint_as_float(a0[j] & 0xffff0000u);
;                                             v[8 + 2 * j] = __uint_as_float(a1[j] << 16); v[9 + 2 * j] = __uint_as_float(a1[j] & 0xffff0000u); } }
; #pragma unroll
;             for (int j = 0; j < 16; ++j) ss += v[j] * v[j];
;             ss += __shfl_xor(ss, 1); ss += __shfl_xor(ss, 2);
;             const float r = rsqrtf(ss * (1.f / 64.f) + 1e-6f);
;             bf16_t* dst = (w == 0 ? p.ksn : p.kwn) + (((size_t)(b * 2 + kvh) * T_) + blk * 64 + t) * 64 + part * 16;
;             u32x4 o0, o1;
; #pragma unroll
;             for (int j = 0; j < 4; ++j) { o0[j] = pk2(v[2 * j] * r * g[2 * j], v[2 * j + 1] * r * g[2 * j + 1]); o1[j] = pk2(v[8 + 2 * j] * r * g[8 + 2 * j], v[9 + 2 * j] * r * g[9 + 2 * j]); }
;             *(u32x4*)dst = o0; *(u32x4*)(dst + 8) = o1;
;         }
; #pragma unroll
;         for (int g3 = 0; g3 < 3; ++g3) {
;             const int h = kvh * 3 + g3;
;             const bf16_t* src = pr + C_QB + h * 64 + part * 16;
;             const float* g = p.q_norm + l * 64 + part * 16;
;             float v[16]; float ss = 0.f;
;             { const u32x4 a0 = *(const u32x4*)src, a1 = *(const u32x4*)(src + 8);
; #pragma unroll
;               for (int j = 0; j < 4; ++j) { v[2 * j] = __uint_as_float(a0[j] << 16); v[2 * j + 1] = __uint_as_float(a0[j] & 0xffff0000u);
;                                             v[8 + 2 * j] = __uint_as_float(a1[j] << 16); v[9 + 2 * j] = __uint_as_float(a1[j] & 0xffff0000u); } }
; #pragma unroll
;             for (int j = 0; j < 16; ++j) ss += v[j] * v[j];
;             ss += __shfl_xor(ss, 1); ss += __shfl_xor(ss, 2);
;             const float r = rsqrtf(ss * (1.f / 64.f) + 1e-6f) * (0.125f * 1.44269504089f);
;             bf16_t* dst = p.qn + (n * 6 + h) * 64 + part * 16;
;             u32x4 o0, o1;
; #pragma unroll
	s_nop 1
	v_mov_b64_e32 v[2:3], v[76:77]
	v_mov_b64_e32 v[4:5], v[78:79]
	s_nop 0
	s_nop 1
	v_mov_b64_e32 v[22:23], v[80:81]
	v_mov_b64_e32 v[24:25], v[82:83]
	s_nop 1
	v_mov_b64_e32 v[36:37], v[84:85]
	v_mov_b64_e32 v[38:39], v[86:87]
	s_nop 1
	v_mov_b64_e32 v[40:41], v[88:89]
	v_mov_b64_e32 v[42:43], v[90:91]
	s_nop 1
	v_mov_b64_e32 v[44:45], v[92:93]
	v_mov_b64_e32 v[46:47], v[94:95]
	s_nop 1
	v_mov_b64_e32 v[48:49], v[96:97]
	v_mov_b64_e32 v[50:51], v[98:99]
	v_lshl_add_u64 v[6:7], s[10:11], 0, v[16:17]
	v_lshl_add_u64 v[6:7], v[6:7], 0, v[188:189]
	v_lshlrev_b32_e32 v74, 16, v2
	v_and_b32_e32 v75, 0xffff0000, v2
	v_lshlrev_b32_e32 v68, 16, v3
	v_and_b32_e32 v69, 0xffff0000, v3
	v_pk_mul_f32 v[2:3], v[74:75], v[74:75]
	v_pk_mul_f32 v[70:71], v[68:69], v[68:69]
	v_add_f32_e32 v2, v2, v3
	v_lshlrev_b32_e32 v62, 16, v4
	v_and_b32_e32 v63, 0xffff0000, v4
	v_add_f32_e32 v2, v70, v2
	v_lshlrev_b32_e32 v56, 16, v5
	v_and_b32_e32 v57, 0xffff0000, v5
	v_pk_mul_f32 v[4:5], v[62:63], v[62:63]
	v_add_f32_e32 v2, v71, v2
	v_add_f32_e32 v2, v4, v2
	v_pk_mul_f32 v[58:59], v[56:57], v[56:57]
	v_add_f32_e32 v2, v5, v2
	v_lshlrev_b32_e32 v72, 16, v22
	v_and_b32_e32 v73, 0xffff0000, v22
	v_add_f32_e32 v2, v58, v2
	v_lshlrev_b32_e32 v64, 16, v23
	v_and_b32_e32 v65, 0xffff0000, v23
	v_pk_mul_f32 v[22:23], v[72:73], v[72:73]
	v_add_f32_e32 v2, v59, v2
	v_add_f32_e32 v2, v22, v2
	v_pk_mul_f32 v[66:67], v[64:65], v[64:65]
	v_add_f32_e32 v2, v23, v2
	v_lshlrev_b32_e32 v60, 16, v24
	v_and_b32_e32 v61, 0xffff0000, v24
	v_add_f32_e32 v2, v66, v2
	v_lshlrev_b32_e32 v52, 16, v25
	v_and_b32_e32 v53, 0xffff0000, v25
	v_pk_mul_f32 v[24:25], v[60:61], v[60:61]
	v_add_f32_e32 v2, v67, v2
	v_add_f32_e32 v2, v24, v2
	v_pk_mul_f32 v[54:55], v[52:53], v[52:53]
	v_add_f32_e32 v2, v25, v2
	v_add_f32_e32 v2, v54, v2
	v_add_f32_e32 v2, v55, v2
	ds_bpermute_b32 v3, v26, v2
	s_waitcnt lgkmcnt(0)
	v_add_f32_e32 v2, v2, v3
	ds_bpermute_b32 v3, v27, v2
	s_waitcnt lgkmcnt(0)
	v_add_f32_e32 v2, v2, v3
	v_fmamk_f32 v2, v2, 0x3c800000, v212
	v_cmp_gt_f32_e32 vcc, s16, v2
	v_mul_f32_e32 v3, 0x4b800000, v2
	s_nop 0
	v_cndmask_b32_e32 v2, v2, v3, vcc
	v_rsq_f32_e32 v2, v2
	s_nop 0
	v_mul_f32_e32 v3, 0x45800000, v2
	v_cndmask_b32_e32 v54, v2, v3, vcc
	v_pk_mul_f32 v[4:5], v[54:55], v[72:73] op_sel_hi:[0,1]
	v_pk_mul_f32 v[4:5], v[40:41], v[4:5]
	v_pk_mul_f32 v[2:3], v[54:55], v[74:75] op_sel_hi:[0,1]
	v_cvt_pk_bf16_f32 v22, v4, v5
	v_pk_mul_f32 v[4:5], v[54:55], v[68:69] op_sel_hi:[0,1]
	v_pk_mul_f32 v[2:3], v[48:49], v[2:3]
	v_pk_mul_f32 v[4:5], v[50:51], v[4:5]
	v_cvt_pk_bf16_f32 v2, v2, v3
	v_cvt_pk_bf16_f32 v3, v4, v5
	v_pk_mul_f32 v[4:5], v[54:55], v[64:65] op_sel_hi:[0,1]
	v_pk_mul_f32 v[4:5], v[42:43], v[4:5]
	v_pk_mul_f32 v[24:25], v[54:55], v[60:61] op_sel_hi:[0,1]
	v_cvt_pk_bf16_f32 v23, v4, v5
	v_pk_mul_f32 v[4:5], v[54:55], v[62:63] op_sel_hi:[0,1]
	v_pk_mul_f32 v[24:25], v[36:37], v[24:25]
	v_pk_mul_f32 v[36:37], v[54:55], v[56:57] op_sel_hi:[0,1]
	v_pk_mul_f32 v[4:5], v[44:45], v[4:5]
	v_pk_mul_f32 v[36:37], v[46:47], v[36:37]
	v_cvt_pk_bf16_f32 v4, v4, v5
	v_cvt_pk_bf16_f32 v5, v36, v37
	v_pk_mul_f32 v[36:37], v[54:55], v[52:53] op_sel_hi:[0,1]
	v_pk_mul_f32 v[36:37], v[38:39], v[36:37]
	v_cvt_pk_bf16_f32 v24, v24, v25
	v_cvt_pk_bf16_f32 v25, v36, v37
	global_store_dwordx4 v[6:7], v[2:5], off
	global_store_dwordx4 v[6:7], v[22:25], off offset:16
	s_nop 1
	v_lshl_add_u64 v[22:23], v[0:1], 0, v[188:189]
	v_lshl_add_u64 v[4:5], v[22:23], 0, s[30:31]
	s_nop 1
	v_mov_b64_e32 v[0:1], v[100:101]
	v_mov_b64_e32 v[2:3], v[102:103]
	s_nop 0
	s_nop 1
	v_mov_b64_e32 v[4:5], v[104:105]
	v_mov_b64_e32 v[6:7], v[106:107]
	s_nop 0
	s_nop 1
	v_mov_b64_e32 v[36:37], v[108:109]
	v_mov_b64_e32 v[38:39], v[110:111]
	s_nop 1
	v_mov_b64_e32 v[40:41], v[112:113]
	v_mov_b64_e32 v[42:43], v[114:115]
	s_nop 1
	v_mov_b64_e32 v[44:45], v[116:117]
	v_mov_b64_e32 v[46:47], v[118:119]
	s_nop 1
	v_mov_b64_e32 v[48:49], v[120:121]
	v_mov_b64_e32 v[50:51], v[122:123]
	v_mov_b32_e32 v24, s8
	v_mov_b32_e32 v25, v189
	v_mad_u64_u32 v[24:25], s[10:11], v20, 6, v[24:25]
	v_mad_i32_i24 v25, v21, 6, v25
	v_lshlrev_b64 v[24:25], 7, v[24:25]
	v_lshl_add_u64 v[24:25], v[14:15], 0, v[24:25]
	s_lshl_b32 s30, s9, 7
	s_add_i32 s8, s8, 2
	v_lshlrev_b32_e32 v74, 16, v0
	v_and_b32_e32 v75, 0xffff0000, v0
	v_lshlrev_b32_e32 v68, 16, v1
	v_and_b32_e32 v69, 0xffff0000, v1
	v_pk_mul_f32 v[0:1], v[74:75], v[74:75]
	v_pk_mul_f32 v[70:71], v[68:69], v[68:69]
	v_add_f32_e32 v0, v0, v1
	v_lshlrev_b32_e32 v62, 16, v2
	v_and_b32_e32 v63, 0xffff0000, v2
	v_add_f32_e32 v0, v70, v0
	v_lshlrev_b32_e32 v56, 16, v3
	v_and_b32_e32 v57, 0xffff0000, v3
	v_pk_mul_f32 v[2:3], v[62:63], v[62:63]
	v_add_f32_e32 v0, v71, v0
	v_add_f32_e32 v0, v2, v0
	v_pk_mul_f32 v[58:59], v[56:57], v[56:57]
	v_add_f32_e32 v0, v3, v0
	v_lshlrev_b32_e32 v72, 16, v4
	v_and_b32_e32 v73, 0xffff0000, v4
	v_add_f32_e32 v0, v58, v0
	v_lshlrev_b32_e32 v64, 16, v5
	v_and_b32_e32 v65, 0xffff0000, v5
	v_pk_mul_f32 v[4:5], v[72:73], v[72:73]
	v_add_f32_e32 v0, v59, v0
	v_add_f32_e32 v0, v4, v0
	v_pk_mul_f32 v[66:67], v[64:65], v[64:65]
	v_add_f32_e32 v0, v5, v0
	v_lshlrev_b32_e32 v60, 16, v6
	v_and_b32_e32 v61, 0xffff0000, v6
	v_add_f32_e32 v0, v66, v0
	v_lshlrev_b32_e32 v52, 16, v7
	v_and_b32_e32 v53, 0xffff0000, v7
	v_pk_mul_f32 v[6:7], v[60:61], v[60:61]
	v_add_f32_e32 v0, v67, v0
	v_add_f32_e32 v0, v6, v0
	v_pk_mul_f32 v[54:55], v[52:53], v[52:53]
	v_add_f32_e32 v0, v7, v0
	v_add_f32_e32 v0, v54, v0
	v_add_f32_e32 v0, v55, v0
	ds_bpermute_b32 v1, v26, v0
	s_waitcnt lgkmcnt(0)
	v_add_f32_e32 v0, v0, v1
	ds_bpermute_b32 v1, v27, v0
	s_waitcnt lgkmcnt(0)
; DI unsigned pk2(float lo, float hi) { f32x2 v = {lo, hi}; bf16x2_t r = __builtin_convertvector(v, bf16x2_t); return __builtin_bit_cast(unsigned, r); }
; DI void phase_nsa_prep(const Params& p, int l, char* smem) {
;     ...
;         for (int g3 = 0; g3 < 3; ++g3) {
;             const int h = kvh * 3 + g3;
;             const bf16_t* src = pr + C_QB + h * 64 + part * 16;
;             const float* g = p.q_norm + l * 64 + part * 16;
;             float v[16]; float ss = 0.f;
;             { const u32x4 a0 = *(const u32x4*)src, a1 = *(const u32x4*)(src + 8);
; #pragma unroll
;               for (int j = 0; j < 4; ++j) { v[2 * j] = __uint_as_float(a0[j] << 16); v[2 * j + 1] = __uint_as_float(a0[j] & 0xffff0000u);
;                                             v[8 + 2 * j] = __uint_as_float(a1[j] << 16); v[9 + 2 * j] = __uint_as_float(a1[j] & 0xffff0000u); } }
; #pragma unroll
;             for (int j = 0; j < 16; ++j) ss += v[j] * v[j];
;             ss += __shfl_xor(ss, 1); ss += __shfl_xor(ss, 2);
;             const float r = rsqrtf(ss * (1.f / 64.f) + 1e-6f) * (0.125f * 1.44269504089f);
;             bf16_t* dst = p.qn + (n * 6 + h) * 64 + part * 16;
;             u32x4 o0, o1;
; #pragma unroll
;             for (int j = 0; j < 4; ++j) { o0[j] = pk2(v[2 * j] * r * g[2 * j], v[2 * j + 1] * r * g[2 * j + 1]); o1[j] = pk2(v[8 + 2 * j] * r * g[8 + 2 * j], v[9 + 2 * j] * r * g[9 + 2 * j]); }
;             *(u32x4*)dst = o0; *(u32x4*)(dst + 8) = o1;
;         }
	v_add_f32_e32 v0, v0, v1
	v_fmamk_f32 v0, v0, 0x3c800000, v212
	v_cmp_gt_f32_e32 vcc, s16, v0
	v_mul_f32_e32 v1, 0x4b800000, v0
	s_nop 0
	v_cndmask_b32_e32 v0, v0, v1, vcc
	v_rsq_f32_e32 v0, v0
	s_nop 0
	v_mul_f32_e32 v1, 0x45800000, v0
	v_cndmask_b32_e32 v0, v0, v1, vcc
	v_mul_f32_e32 v54, 0x3e38aa3b, v0
	v_pk_mul_f32 v[2:3], v[54:55], v[72:73] op_sel_hi:[0,1]
	v_pk_mul_f32 v[2:3], v[40:41], v[2:3]
	v_pk_mul_f32 v[0:1], v[54:55], v[74:75] op_sel_hi:[0,1]
	v_cvt_pk_bf16_f32 v4, v2, v3
	v_pk_mul_f32 v[2:3], v[54:55], v[68:69] op_sel_hi:[0,1]
	v_pk_mul_f32 v[0:1], v[48:49], v[0:1]
	v_pk_mul_f32 v[2:3], v[50:51], v[2:3]
	v_cvt_pk_bf16_f32 v0, v0, v1
	v_cvt_pk_bf16_f32 v1, v2, v3
	v_pk_mul_f32 v[2:3], v[54:55], v[64:65] op_sel_hi:[0,1]
	v_pk_mul_f32 v[2:3], v[42:43], v[2:3]
	v_pk_mul_f32 v[6:7], v[54:55], v[60:61] op_sel_hi:[0,1]
	v_cvt_pk_bf16_f32 v5, v2, v3
	v_pk_mul_f32 v[2:3], v[54:55], v[62:63] op_sel_hi:[0,1]
	v_pk_mul_f32 v[6:7], v[36:37], v[6:7]
	v_pk_mul_f32 v[36:37], v[54:55], v[56:57] op_sel_hi:[0,1]
	v_pk_mul_f32 v[2:3], v[44:45], v[2:3]
	v_pk_mul_f32 v[36:37], v[46:47], v[36:37]
	v_cvt_pk_bf16_f32 v2, v2, v3
	v_cvt_pk_bf16_f32 v3, v36, v37
	v_pk_mul_f32 v[36:37], v[54:55], v[52:53] op_sel_hi:[0,1]
	v_pk_mul_f32 v[36:37], v[38:39], v[36:37]
	v_cvt_pk_bf16_f32 v6, v6, v7
	v_cvt_pk_bf16_f32 v7, v36, v37
	global_store_dwordx4 v[24:25], v[0:3], off
	global_store_dwordx4 v[24:25], v[4:7], off offset:16
	v_mov_b32_e32 v24, s9
	v_mov_b32_e32 v25, v189
	v_lshl_add_u64 v[4:5], v[22:23], 0, s[30:31]
	s_nop 1
	v_mov_b64_e32 v[0:1], v[124:125]
	v_mov_b64_e32 v[2:3], v[126:127]
	s_nop 0
	s_nop 1
	v_mov_b64_e32 v[4:5], v[128:129]
	v_mov_b64_e32 v[6:7], v[130:131]
	s_nop 0
	s_nop 1
	v_mov_b64_e32 v[36:37], v[132:133]
	v_mov_b64_e32 v[38:39], v[134:135]
	s_nop 1
	v_mov_b64_e32 v[40:41], v[136:137]
	v_mov_b64_e32 v[42:43], v[138:139]
	s_nop 1
	v_mov_b64_e32 v[44:45], v[140:141]
	v_mov_b64_e32 v[46:47], v[142:143]
	s_nop 1
	v_mov_b64_e32 v[48:49], v[144:145]
	v_mov_b64_e32 v[50:51], v[146:147]
	v_mad_u64_u32 v[24:25], s[10:11], v20, 6, v[24:25]
	v_mad_i32_i24 v25, v21, 6, v25
	v_lshlrev_b64 v[24:25], 7, v[24:25]
	v_lshl_add_u64 v[24:25], v[14:15], 0, v[24:25]
	s_lshl_b32 s30, s8, 7
	v_lshlrev_b32_e32 v74, 16, v0
	v_and_b32_e32 v75, 0xffff0000, v0
	v_lshlrev_b32_e32 v68, 16, v1
	v_and_b32_e32 v69, 0xffff0000, v1
	v_pk_mul_f32 v[0:1], v[74:75], v[74:75]
	v_pk_mul_f32 v[70:71], v[68:69], v[68:69]
	v_add_f32_e32 v0, v0, v1
	v_lshlrev_b32_e32 v62, 16, v2
	v_and_b32_e32 v63, 0xffff0000, v2
	v_add_f32_e32 v0, v70, v0
	v_lshlrev_b32_e32 v56, 16, v3
	v_and_b32_e32 v57, 0xffff0000, v3
	v_pk_mul_f32 v[2:3], v[62:63], v[62:63]
	v_add_f32_e32 v0, v71, v0
	v_add_f32_e32 v0, v2, v0
	v_pk_mul_f32 v[58:59], v[56:57], v[56:57]
	v_add_f32_e32 v0, v3, v0
	v_lshlrev_b32_e32 v72, 16, v4
	v_and_b32_e32 v73, 0xffff0000, v4
	v_add_f32_e32 v0, v58, v0
	v_lshlrev_b32_e32 v64, 16, v5
	v_and_b32_e32 v65, 0xffff0000, v5
	v_pk_mul_f32 v[4:5], v[72:73], v[72:73]
	v_add_f32_e32 v0, v59, v0
	v_add_f32_e32 v0, v4, v0
	v_pk_mul_f32 v[66:67], v[64:65], v[64:65]
	v_add_f32_e32 v0, v5, v0
	v_lshlrev_b32_e32 v60, 16, v6
	v_and_b32_e32 v61, 0xffff0000, v6
	v_add_f32_e32 v0, v66, v0
	v_lshlrev_b32_e32 v52, 16, v7
	v_and_b32_e32 v53, 0xffff0000, v7
	v_pk_mul_f32 v[6:7], v[60:61], v[60:61]
	v_add_f32_e32 v0, v67, v0
	v_add_f32_e32 v0, v6, v0
	v_pk_mul_f32 v[54:55], v[52:53], v[52:53]
	v_add_f32_e32 v0, v7, v0
	v_add_f32_e32 v0, v54, v0
	v_add_f32_e32 v0, v55, v0
	ds_bpermute_b32 v1, v26, v0
	s_waitcnt lgkmcnt(0)
	v_add_f32_e32 v0, v0, v1
	ds_bpermute_b32 v1, v27, v0
	s_waitcnt lgkmcnt(0)
	v_add_f32_e32 v0, v0, v1
	v_fmamk_f32 v0, v0, 0x3c800000, v212
	v_cmp_gt_f32_e32 vcc, s16, v0
	v_mul_f32_e32 v1, 0x4b800000, v0
	s_nop 0
	v_cndmask_b32_e32 v0, v0, v1, vcc
	v_rsq_f32_e32 v0, v0
	s_nop 0
	v_mul_f32_e32 v1, 0x45800000, v0
	v_cndmask_b32_e32 v0, v0, v1, vcc
	v_mul_f32_e32 v54, 0x3e38aa3b, v0
	v_pk_mul_f32 v[2:3], v[54:55], v[72:73] op_sel_hi:[0,1]
	v_pk_mul_f32 v[2:3], v[40:41], v[2:3]
	v_pk_mul_f32 v[0:1], v[54:55], v[74:75] op_sel_hi:[0,1]
	v_cvt_pk_bf16_f32 v4, v2, v3
	v_pk_mul_f32 v[2:3], v[54:55], v[68:69] op_sel_hi:[0,1]
	v_pk_mul_f32 v[0:1], v[48:49], v[0:1]
	v_pk_mul_f32 v[2:3], v[50:51], v[2:3]
	v_cvt_pk_bf16_f32 v0, v0, v1
	v_cvt_pk_bf16_f32 v1, v2, v3
	v_pk_mul_f32 v[2:3], v[54:55], v[64:65] op_sel_hi:[0,1]
	v_pk_mul_f32 v[2:3], v[42:43], v[2:3]
	v_pk_mul_f32 v[6:7], v[54:55], v[60:61] op_sel_hi:[0,1]
	v_cvt_pk_bf16_f32 v5, v2, v3
	v_pk_mul_f32 v[2:3], v[54:55], v[62:63] op_sel_hi:[0,1]
	v_pk_mul_f32 v[6:7], v[36:37], v[6:7]
	v_pk_mul_f32 v[36:37], v[54:55], v[56:57] op_sel_hi:[0,1]
	v_pk_mul_f32 v[2:3], v[44:45], v[2:3]
	v_pk_mul_f32 v[36:37], v[46:47], v[36:37]
	v_cvt_pk_bf16_f32 v2, v2, v3
	v_cvt_pk_bf16_f32 v3, v36, v37
	v_pk_mul_f32 v[36:37], v[54:55], v[52:53] op_sel_hi:[0,1]
	v_pk_mul_f32 v[36:37], v[38:39], v[36:37]
	v_cvt_pk_bf16_f32 v6, v6, v7
	v_cvt_pk_bf16_f32 v7, v36, v37
	global_store_dwordx4 v[24:25], v[0:3], off
	global_store_dwordx4 v[24:25], v[4:7], off offset:16
	s_nop 1
	v_lshl_add_u64 v[4:5], v[22:23], 0, s[30:31]
	s_nop 1
	v_mov_b64_e32 v[0:1], v[148:149]
	v_mov_b64_e32 v[2:3], v[150:151]
	s_nop 0
	s_nop 1
	v_mov_b64_e32 v[4:5], v[152:153]
	v_mov_b64_e32 v[6:7], v[154:155]
	v_mov_b32_e32 v22, s8
	v_mov_b32_e32 v23, v189
	v_mad_u64_u32 v[22:23], s[8:9], v20, 6, v[22:23]
	v_mad_i32_i24 v23, v21, 6, v23
	v_lshlrev_b64 v[20:21], 7, v[22:23]
	s_nop 1
	v_mov_b64_e32 v[22:23], v[156:157]
	v_mov_b64_e32 v[24:25], v[158:159]
	s_nop 1
	v_mov_b64_e32 v[36:37], v[160:161]
	v_mov_b64_e32 v[38:39], v[162:163]
	s_nop 1
	v_mov_b64_e32 v[40:41], v[164:165]
; DI void phase_nsa_prep(const Params& p, int l, char* smem) {
;     ...
;         for (int g3 = 0; g3 < 3; ++g3) {
;             const int h = kvh * 3 + g3;
;             const bf16_t* src = pr + C_QB + h * 64 + part * 16;
;             const float* g = p.q_norm + l * 64 + part * 16;
;             float v[16]; float ss = 0.f;
;             { const u32x4 a0 = *(const u32x4*)src, a1 = *(const u32x4*)(src + 8);
; #pragma unroll
;               for (int j = 0; j < 4; ++j) { v[2 * j] = __uint_as_float(a0[j] << 16); v[2 * j + 1] = __uint_as_float(a0[j] & 0xffff0000u);
;                                             v[8 + 2 * j] = __uint_as_float(a1[j] << 16); v[9 + 2 * j] = __uint_as_float(a1[j] & 0xffff0000u); } }
; #pragma unroll
;             for (int j = 0; j < 16; ++j) ss += v[j] * v[j];
;             ss += __shfl_xor(ss, 1); ss += __shfl_xor(ss, 2);
;             const float r = rsqrtf(ss * (1.f / 64.f) + 1e-6f) * (0.125f * 1.44269504089f);
;             bf16_t* dst = p.qn + (n * 6 + h) * 64 + part * 16;
;             u32x4 o0, o1;
; #pragma unroll
;             for (int j = 0; j < 4; ++j) { o0[j] = pk2(v[2 * j] * r * g[2 * j], v[2 * j + 1] * r * g[2 * j + 1]); o1[j] = pk2(v[8 + 2 * j] * r * g[8 + 2 * j], v[9 + 2 * j] * r * g[9 + 2 * j]); }
;             *(u32x4*)dst = o0; *(u32x4*)(dst + 8) = o1;
;         }
; #pragma unroll
;         for (int w = 0; w < 2; ++w) {
;             const bf16_t* src = pr + C_KV + (w == 0 ? 384 : 640) + kvh * 64 + part * 16;
;             { const u32x4 a0 = *(const u32x4*)src, a1 = *(const u32x4*)(src + 8);
; #pragma unroll
;               for (int j = 0; j < 4; ++j) {
;                   tr[w * 64 * 66 + (part * 16 + 2 * j) * 66 + t] = (bf16_t)(a0[j] & 0xffffu); tr[w * 64 * 66 + (part * 16 + 2 * j + 1) * 66 + t] = (bf16_t)(a0[j] >> 16);
;                   tr[w * 64 * 66 + (part * 16 + 8 + 2 * j) * 66 + t] = (bf16_t)(a1[j] & 0xffffu); tr[w * 64 * 66 + (part * 16 + 9 + 2 * j) * 66 + t] = (bf16_t)(a1[j] >> 16); } }
;         }
;         __syncthreads();
; #pragma unroll
;         for (int w = 0; w < 2; ++w) {
;             const int d = t;
;             u32x4 o0, o1;
; #pragma unroll
;             for (int j = 0; j < 8; ++j) {
;                 const int p0 = part * 16 + 2 * j;
;                 const unsigned a = (unsigned)tr[w * 64 * 66 + d * 66 + PERM(p0)] | ((unsigned)tr[w * 64 * 66 + d * 66 + PERM(p0 + 1)] << 16);
	v_mov_b64_e32 v[42:43], v[166:167]
	s_nop 1
	v_mov_b64_e32 v[44:45], v[168:169]
	v_mov_b64_e32 v[46:47], v[170:171]
	v_lshl_add_u64 v[20:21], v[14:15], 0, v[20:21]
	s_add_u32 s8, s56, s4
	s_addc_u32 s9, s57, s5
	s_add_u32 s4, s58, s4
	s_addc_u32 s5, s59, s5
	s_add_i32 s7, s7, s14
	s_add_i32 s6, s6, s15
	s_cmpk_lt_i32 s7, 0x400
	v_lshlrev_b32_e32 v70, 16, v0
	v_and_b32_e32 v71, 0xffff0000, v0
	v_lshlrev_b32_e32 v64, 16, v1
	v_and_b32_e32 v65, 0xffff0000, v1
	v_pk_mul_f32 v[0:1], v[70:71], v[70:71]
	v_pk_mul_f32 v[66:67], v[64:65], v[64:65]
	v_add_f32_e32 v0, v0, v1
	v_lshlrev_b32_e32 v58, 16, v2
	v_and_b32_e32 v59, 0xffff0000, v2
	v_add_f32_e32 v0, v66, v0
	v_lshlrev_b32_e32 v52, 16, v3
	v_and_b32_e32 v53, 0xffff0000, v3
	v_pk_mul_f32 v[2:3], v[58:59], v[58:59]
	v_add_f32_e32 v0, v67, v0
	v_add_f32_e32 v0, v2, v0
	v_pk_mul_f32 v[54:55], v[52:53], v[52:53]
	v_add_f32_e32 v0, v3, v0
	v_lshlrev_b32_e32 v68, 16, v4
	v_and_b32_e32 v69, 0xffff0000, v4
	v_add_f32_e32 v0, v54, v0
	v_lshlrev_b32_e32 v60, 16, v5
	v_and_b32_e32 v61, 0xffff0000, v5
	v_pk_mul_f32 v[4:5], v[68:69], v[68:69]
	v_add_f32_e32 v0, v55, v0
	v_add_f32_e32 v0, v4, v0
	v_pk_mul_f32 v[62:63], v[60:61], v[60:61]
	v_add_f32_e32 v0, v5, v0
	v_lshlrev_b32_e32 v56, 16, v6
	v_and_b32_e32 v57, 0xffff0000, v6
	v_add_f32_e32 v0, v62, v0
	v_lshlrev_b32_e32 v48, 16, v7
	v_and_b32_e32 v49, 0xffff0000, v7
	v_pk_mul_f32 v[6:7], v[56:57], v[56:57]
	v_add_f32_e32 v0, v63, v0
	v_add_f32_e32 v0, v6, v0
	v_pk_mul_f32 v[50:51], v[48:49], v[48:49]
	v_add_f32_e32 v0, v7, v0
	v_add_f32_e32 v0, v50, v0
	v_add_f32_e32 v0, v51, v0
	ds_bpermute_b32 v1, v26, v0
	s_waitcnt lgkmcnt(0)
	v_add_f32_e32 v0, v0, v1
	ds_bpermute_b32 v1, v27, v0
	s_waitcnt lgkmcnt(0)
	v_add_f32_e32 v0, v0, v1
	v_fmamk_f32 v0, v0, 0x3c800000, v212
	v_cmp_gt_f32_e32 vcc, s16, v0
	v_mul_f32_e32 v1, 0x4b800000, v0
	s_nop 0
	v_cndmask_b32_e32 v0, v0, v1, vcc
	v_rsq_f32_e32 v0, v0
	s_nop 0
	v_mul_f32_e32 v1, 0x45800000, v0
	v_cndmask_b32_e32 v0, v0, v1, vcc
	v_mul_f32_e32 v50, 0x3e38aa3b, v0
	v_pk_mul_f32 v[2:3], v[50:51], v[68:69] op_sel_hi:[0,1]
	v_pk_mul_f32 v[2:3], v[36:37], v[2:3]
	v_pk_mul_f32 v[0:1], v[50:51], v[70:71] op_sel_hi:[0,1]
	v_cvt_pk_bf16_f32 v4, v2, v3
	v_pk_mul_f32 v[2:3], v[50:51], v[64:65] op_sel_hi:[0,1]
	v_pk_mul_f32 v[0:1], v[44:45], v[0:1]
	v_pk_mul_f32 v[2:3], v[46:47], v[2:3]
	v_cvt_pk_bf16_f32 v0, v0, v1
	v_cvt_pk_bf16_f32 v1, v2, v3
	v_pk_mul_f32 v[2:3], v[50:51], v[60:61] op_sel_hi:[0,1]
	v_pk_mul_f32 v[2:3], v[38:39], v[2:3]
	v_pk_mul_f32 v[6:7], v[50:51], v[56:57] op_sel_hi:[0,1]
	v_cvt_pk_bf16_f32 v5, v2, v3
	v_pk_mul_f32 v[2:3], v[50:51], v[58:59] op_sel_hi:[0,1]
	v_pk_mul_f32 v[6:7], v[22:23], v[6:7]
	v_pk_mul_f32 v[22:23], v[50:51], v[52:53] op_sel_hi:[0,1]
	v_pk_mul_f32 v[2:3], v[40:41], v[2:3]
	v_pk_mul_f32 v[22:23], v[42:43], v[22:23]
	v_cvt_pk_bf16_f32 v2, v2, v3
	v_cvt_pk_bf16_f32 v3, v22, v23
	v_pk_mul_f32 v[22:23], v[50:51], v[48:49] op_sel_hi:[0,1]
	v_pk_mul_f32 v[22:23], v[24:25], v[22:23]
	v_cvt_pk_bf16_f32 v6, v6, v7
	v_cvt_pk_bf16_f32 v7, v22, v23
	global_store_dwordx4 v[20:21], v[0:3], off
	global_store_dwordx4 v[20:21], v[4:7], off offset:16
	s_nop 1
	v_mov_b64_e32 v[0:1], v[172:173]
	v_mov_b64_e32 v[2:3], v[174:175]
	s_nop 0
	s_nop 1
	v_mov_b64_e32 v[4:5], v[176:177]
	v_mov_b64_e32 v[6:7], v[178:179]
	ds_write_b16 v28, v0
	ds_write_b16_d16_hi v29, v0 offset:132
	ds_write_b16 v29, v4 offset:1056
	ds_write_b16_d16_hi v29, v4 offset:1188
	ds_write_b16 v29, v1 offset:264
	ds_write_b16_d16_hi v30, v1 offset:132
	ds_write_b16 v30, v5 offset:1056
	ds_write_b16_d16_hi v30, v5 offset:1188
	ds_write_b16 v28, v2 offset:528
	ds_write_b16_d16_hi v29, v2 offset:660
	ds_write_b16 v29, v6 offset:1584
	ds_write_b16_d16_hi v29, v6 offset:1716
	ds_write_b16 v30, v3 offset:528
	ds_write_b16_d16_hi v31, v3 offset:132
	ds_write_b16 v31, v7 offset:1056
	ds_write_b16_d16_hi v31, v7 offset:1188
	s_nop 1
	v_mov_b64_e32 v[0:1], v[180:181]
	v_mov_b64_e32 v[2:3], v[182:183]
	s_nop 1
	v_mov_b64_e32 v[4:5], v[184:185]
	v_mov_b64_e32 v[6:7], v[186:187]
	ds_write_b16 v28, v0 offset:8448
	ds_write_b16_d16_hi v29, v0 offset:8580
	ds_write_b16 v29, v4 offset:9504
	ds_write_b16_d16_hi v29, v4 offset:9636
	ds_write_b16 v29, v1 offset:8712
	ds_write_b16_d16_hi v30, v1 offset:8580
	ds_write_b16 v30, v5 offset:9504
	ds_write_b16_d16_hi v30, v5 offset:9636
	ds_write_b16 v28, v2 offset:8976
	ds_write_b16_d16_hi v29, v2 offset:9108
	ds_write_b16 v29, v6 offset:10032
	ds_write_b16_d16_hi v29, v6 offset:10164
	ds_write_b16 v30, v3 offset:8976
	ds_write_b16_d16_hi v31, v3 offset:8580
	ds_write_b16 v31, v7 offset:9504
	ds_write_b16_d16_hi v31, v7 offset:9636
	s_waitcnt lgkmcnt(0)
	s_barrier
	ds_read2_b32 v[2:3], v33 offset1:8
	ds_read2_b32 v[18:19], v32 offset1:2
	ds_read2_b32 v[20:21], v32 offset0:8 offset1:10
	ds_read2st64_b32 v[4:5], v34 offset1:33
	ds_read2st64_b32 v[6:7], v35 offset1:33
	v_lshl_add_u64 v[22:23], s[8:9], 0, v[16:17]
	s_waitcnt lgkmcnt(4)
	v_mov_b32_e32 v1, v2
	s_waitcnt lgkmcnt(3)
	v_mov_b32_e32 v0, v18
	s_waitcnt lgkmcnt(2)
	v_mov_b32_e32 v2, v20
	v_lshl_add_u64 v[22:23], v[22:23], 0, v[188:189]
	v_mov_b32_e32 v18, v19
	s_waitcnt lgkmcnt(1)
	v_mov_b32_e32 v19, v4
	v_mov_b32_e32 v20, v21
	s_waitcnt lgkmcnt(0)
	v_mov_b32_e32 v21, v6
	global_store_dwordx4 v[22:23], v[0:3], off
	global_store_dwordx4 v[22:23], v[18:21], off offset:16
	v_lshl_add_u64 v[16:17], s[4:5], 0, v[16:17]
	v_add_u32_e32 v0, 0x2000, v32
	v_add_u32_e32 v1, 0x2000, v33
	ds_read2_b32 v[18:19], v0 offset0:64 offset1:66
	ds_read2_b32 v[2:3], v1 offset0:64 offset1:72
	ds_read2_b32 v[20:21], v0 offset0:72 offset1:74
	v_lshl_add_u64 v[16:17], v[16:17], 0, v[188:189]
	s_waitcnt lgkmcnt(2)
	v_mov_b32_e32 v0, v18
	s_waitcnt lgkmcnt(1)
	v_mov_b32_e32 v1, v2
	s_waitcnt lgkmcnt(0)
	v_mov_b32_e32 v2, v20
	v_mov_b32_e32 v4, v19
	v_mov_b32_e32 v6, v21
	global_store_dwordx4 v[16:17], v[0:3], off
	global_store_dwordx4 v[16:17], v[4:7], off offset:16
	s_barrier
	s_cbranch_scc1 .LBB0_350
	s_mov_b32 s78, 0x800000
